# attn1 prompt loop: qb-split software pipeline (softmax of one query half overlapped with MFMAs of the other), per-qb lazy rescale, no static setprio
# speedup vs baseline: 1.0321x; 1.0291x over previous
; #define ATT_GLOAD(t_) do { const size_t row_ = (size_t)(A.k_row0 + 64 * (t_)); \
;         kreg = *(const u32x4*)(A.K + (row_ + lkey) * A.k_stride + 8 * lpc); vreg = *(const u32x4*)(A.V + (row_ + lkey) * A.v_stride + 8 * lpc); \
;         if (DQ == 96 && tid < 256) k2reg = *(const u32x4*)(A.K2 + (row_ + l2key) * 32 + 8 * l2pc); } while (0)
; #define ATT_LSTORE(buf_) do { LAS unsigned char* kb_ = lds + (buf_) * KBUF; LAS unsigned char* vb_ = lds + 2 * KBUF + (buf_) * VBUF; \
;         *(LAS u32x4*)(kb_ + (lkey * KSTR + 8 * lpc) * 2) = kreg; *(LAS u32x4*)(vb_ + (lkey * VROW + 8 * lpc) * 2) = vreg; \
;         if (DQ == 96 && tid < 256) *(LAS u32x4*)(kb_ + (l2key * KSTR + 64 + 8 * l2pc) * 2) = k2reg; } while (0)
; template <int DQ, bool BIAS, bool TAIL>
; __device__ __forceinline__ void attn_item(const AttnItem& A, LAS unsigned char* lds, int wave_s_) {
;     ...
;     f32x16 o[2][2];
;     float zinit = 0.f; asm volatile("" : "+v"(zinit));
;     const f32x16 zero16v = {0.f, 0.f, 0.f, 0.f, 0.f, 0.f, 0.f, 0.f, 0.f, 0.f, 0.f, 0.f, 0.f, 0.f, 0.f, 0.f};
;     float mref[2] = {A.m0, A.m0};
; #pragma unroll
;     for (int qb = 0; qb < 2; ++qb)
; #pragma unroll
;         for (int i = 0; i < 16; ++i) { o[0][qb][i] = zinit; o[1][qb][i] = zinit; }
;     float lrun[2] = {hi == 0 ? A.l0 : 0.f, hi == 0 ? A.l0 : 0.f};
;     bool first = A.l0 == 0.f;
;     const int lkey = tid >> 3, lpc = tid & 7, l2key = tid >> 2, l2pc = tid & 3;
;     u32x4 kreg, k2reg, vreg;
;     ...
;     ATT_GLOAD(A.t_lo); ATT_LSTORE(0);
;     __syncthreads();
;     const int i16 = lane & 15, vlane_off = ((4 * hi + (i16 >> 2)) * VROW + 16 * ((lane >> 4) & 1) + 4 * (i16 & 3)) * 2;
;     const int koff = (r32 * KSTR + 8 * hi) * 2;
;     if (w < 4) __builtin_amdgcn_s_setprio(2);
;     int buf = 0;
.LBB0_1468:
	s_or_b64 exec, exec, s[4:5]
	s_movk_i32 s1, 0x68
	v_mad_u64_u32 v[14:15], s[4:5], v206, s1, v[10:11]
	v_lshlrev_b32_e32 v224, 1, v14
	v_add_u32_e32 v1, 0, v224
	s_waitcnt vmcnt(1)
	ds_write_b128 v1, v[6:9]
	v_lshlrev_b32_e32 v1, 5, v206
	v_sub_u32_e32 v1, v14, v1
	s_movk_i32 s1, 0xd0
	v_lshl_add_u32 v225, v1, 1, 0
	v_mul_lo_u32 v226, v208, s1
	s_waitcnt vmcnt(0)
	ds_write_b128 v225, v[2:5] offset:26624
	s_and_saveexec_b64 s[4:5], s[6:7]
	v_add3_u32 v1, 0, v210, v226
	ds_write_b128 v1, v[144:147] offset:128
	s_or_b64 exec, exec, s[4:5]
	s_cmp_gt_i32 s8, 3
	s_mov_b32 s33, 0xffff
	s_waitcnt lgkmcnt(0)
	s_barrier
	s_cbranch_scc1 .LBB0_1472
	s_setprio 0
.LBB0_1472:
	v_lshlrev_b32_e32 v222, 2, v12
	v_lshrrev_b32_e32 v1, 2, v11
	v_and_b32_e32 v2, 16, v11
	v_lshlrev_b32_e32 v3, 2, v11
	v_and_b32_e32 v17, 63, v11
	v_and_or_b32 v1, v1, 3, v222
	v_and_or_b32 v2, v3, 12, v2
	s_movk_i32 s1, 0x48
	v_mad_u32_u24 v18, v1, s1, v2
	v_mul_u32_u24_e32 v19, 0xd0, v220
	v_mov_b32_e32 v14, v0
	v_mov_b32_e32 v15, v0
	v_cmp_gt_u32_e64 s[4:5], 32, v17
	v_mov_b32_e32 v17, v197
	v_mov_b32_e32 v1, v0
	v_mov_b32_e32 v2, v0
	v_mov_b32_e32 v3, v0
	v_mov_b32_e32 v4, v0
	v_mov_b32_e32 v5, v0
	v_mov_b32_e32 v6, v0
	v_mov_b32_e32 v7, v0
	v_mov_b32_e32 v8, v0
	v_mov_b32_e32 v9, v0
	v_mov_b32_e32 v10, v0
	v_mov_b32_e32 v11, v0
	v_mov_b32_e32 v12, v0
	v_mov_b32_e32 v13, v0
	v_add3_u32 v228, 0, v196, v19
	v_lshl_add_u32 v227, v18, 1, 0
	v_lshl_add_u64 v[214:215], s[46:47], 0, v[16:17]
	v_lshl_add_u64 v[216:217], s[48:49], 0, v[16:17]
	v_mov_b32_e32 v211, v197
	v_mov_b32_e32 v196, v197
	v_mov_b64_e32 v[46:47], v[14:15]
	v_mov_b64_e32 v[30:31], v[14:15]
	v_mov_b64_e32 v[62:63], v[14:15]
	s_min_i32 s1, s20, s66
	v_lshl_add_u64 v[218:219], s[40:41], 0, v[210:211]
	s_add_i32 s18, s72, 64
	s_mov_b32 s21, 0
	s_mov_b64 s[16:17], -1
	s_mov_b64 s[100:101], -1
	v_mov_b32_e32 v223, 0
	v_mov_b64_e32 v[44:45], v[12:13]
	v_mov_b64_e32 v[42:43], v[10:11]
	v_mov_b64_e32 v[40:41], v[8:9]
	v_mov_b64_e32 v[38:39], v[6:7]
	v_mov_b64_e32 v[36:37], v[4:5]
	v_mov_b64_e32 v[34:35], v[2:3]
	v_mov_b64_e32 v[32:33], v[0:1]
	v_mov_b64_e32 v[28:29], v[12:13]
	v_mov_b64_e32 v[26:27], v[10:11]
	v_mov_b64_e32 v[24:25], v[8:9]
	v_mov_b64_e32 v[22:23], v[6:7]
	v_mov_b64_e32 v[20:21], v[4:5]
	v_mov_b64_e32 v[18:19], v[2:3]
	v_mov_b64_e32 v[16:17], v[0:1]
	v_mov_b64_e32 v[60:61], v[12:13]
	v_mov_b64_e32 v[58:59], v[10:11]
	v_mov_b64_e32 v[56:57], v[8:9]
	v_mov_b64_e32 v[54:55], v[6:7]
	v_mov_b64_e32 v[52:53], v[4:5]
	v_mov_b64_e32 v[50:51], v[2:3]
	v_mov_b64_e32 v[48:49], v[0:1]
	v_mov_b32_e32 v211, 0
	s_mov_b32 s22, 0
	v_mov_b64_e32 v[212:213], v[196:197]
	s_branch .LBB0_1474

; #define LAS __attribute__((address_space(3)))
; template <int DQ, bool BIAS, bool TAIL>
; __device__ __forceinline__ void attn_item(const AttnItem& A, LAS unsigned char* lds, int wave_s_) {
;     ...
;         if (act) {
; #pragma unroll
;             for (int kbk = 0; kbk < 2; ++kbk) {
;                 __builtin_amdgcn_sched_barrier(0);
;                 f32x16 s[2];
;                 s[0] = MFMA32(kf[0], qf[0][0], zero16v); s[1] = MFMA32(kf[0], qf[1][0], zero16v);
; #pragma unroll
;                 for (int kk = 1; kk < NKK; ++kk) { s[0] = MFMA32(kf[kk], qf[0][kk], s[0]); s[1] = MFMA32(kf[kk], qf[1][kk], s[1]); }
;                 s16x4 vlo[2][2], vhi[2][2];
; #pragma unroll
;                 for (int st = 0; st < 2; ++st)
; #pragma unroll
;                     for (int d = 0; d < 2; ++d) { const LAS unsigned char* vp = vb + ((32 * kbk + 16 * st) * VROW + 32 * d) * 2; vlo[st][d] = vtr(vp); vhi[st][d] = vtr(vp + 8 * VROW * 2); }
;                 __builtin_amdgcn_sched_barrier(0);
;                 float mx[2];
; #pragma unroll
;                 for (int qb = 0; qb < 2; ++qb) {
;                     if (BIAS || TAIL) {
;                         const int qk = A.q_kidx0 + 64 * w + 32 * qb + r32;
; #pragma unroll
;                         for (int i = 0; i < 16; ++i) { const int kidx = 64 * t + 32 * kbk + crow(i, hi);
;                             float v = s[qb][i]; if (BIAS) v += lut[kidx - qk + LUT0]; if (TAIL && kidx >= A.nkeys) v = -1.0e30f; s[qb][i] = v; }
;                     }
;                     const float t0 = max3f(s[qb][0], s[qb][1], s[qb][2]), t1 = max3f(s[qb][3], s[qb][4], s[qb][5]), t2 = max3f(s[qb][6], s[qb][7], s[qb][8]),
;                                 t3 = max3f(s[qb][9], s[qb][10], s[qb][11]), t4 = max3f(s[qb][12], s[qb][13], s[qb][14]);
;                     const float m = max3f(max3f(t0, t1, t2), max3f(t3, t4, s[qb][15]), t0);
;                     mx[qb] = swapmax(m, hi) - mref[qb];
;                 }
;                 const bool need0 = first || mx[0] > RESCALE_THR, need1 = first || mx[1] > RESCALE_THR;
;                 if (__builtin_amdgcn_ballot_w64(need0 || need1) != 0ull) {
; #pragma unroll
;                     for (int qb = 0; qb < 2; ++qb) {
;                         const float delta = (qb == 0 ? need0 : need1) ? mx[qb] : 0.f, alpha = __builtin_amdgcn_exp2f(-delta);
; #pragma unroll
.LBB0_1478:
	s_or_b64 exec, exec, s[10:11]
	s_andn2_b64 vcc, exec, s[8:9]
	s_cbranch_vccnz .LBB0_1484
	s_mul_i32 s8, s21, 0x2400
	v_add_u32_e32 v229, s8, v227
	s_waitcnt lgkmcnt(5)
	v_mfma_f32_32x32x16_bf16 v[80:95], v[176:179], v[96:99], 0
	ds_read_b64_tr_b16 v[192:193], v229 offset:26624
	ds_read_b64_tr_b16 v[194:195], v229 offset:27776
	ds_read_b64_tr_b16 v[188:189], v229 offset:26688
	ds_read_b64_tr_b16 v[190:191], v229 offset:27840
	ds_read_b64_tr_b16 v[184:185], v229 offset:28928
	ds_read_b64_tr_b16 v[186:187], v229 offset:30080
	ds_read_b64_tr_b16 v[180:181], v229 offset:28992
	ds_read_b64_tr_b16 v[182:183], v229 offset:30144
	s_waitcnt lgkmcnt(12)
	v_mfma_f32_32x32x16_bf16 v[80:95], v[172:175], v[100:103], v[80:95]
	s_waitcnt lgkmcnt(11)
	v_mfma_f32_32x32x16_bf16 v[80:95], v[168:171], v[104:107], v[80:95]
	s_waitcnt lgkmcnt(10)
	v_mfma_f32_32x32x16_bf16 v[80:95], v[164:167], v[108:111], v[80:95]
	s_waitcnt lgkmcnt(9)
	v_mfma_f32_32x32x16_bf16 v[80:95], v[160:163], v[112:115], v[80:95]
	s_waitcnt lgkmcnt(8)
	v_mfma_f32_32x32x16_bf16 v[80:95], v[156:159], v[116:119], v[80:95]
	v_mfma_f32_32x32x16_bf16 v[64:79], v[176:179], v[120:123], 0
	ds_read_b128 v[230:233], v196 offset:6656
	ds_read_b128 v[238:241], v196 offset:6688
	ds_read_b128 v[246:249], v196 offset:6720
	ds_read_b128 v[250:253], v196 offset:6752
	ds_read_b128 v[176:179], v196 offset:6784
	v_mfma_f32_32x32x16_bf16 v[64:79], v[172:175], v[124:127], v[64:79]
	ds_read_b128 v[172:175], v196 offset:6816
	s_nop 3
	v_max3_f32 v198, v80, v81, v82
	v_max3_f32 v199, v83, v84, v85
	v_max3_f32 v204, v86, v87, v88
	v_max3_f32 v205, v89, v90, v91
	v_max3_f32 v234, v92, v93, v94
	v_max3_f32 v199, v198, v199, v204
	v_max3_f32 v205, v205, v234, v95
	v_max3_f32 v204, v199, v205, v198
	v_mfma_f32_32x32x16_bf16 v[64:79], v[168:171], v[128:131], v[64:79]
	v_mov_b32_e32 v234, v204
	s_nop 1
	v_permlane32_swap_b32_e32 v234, v204
	v_max_f32_e32 v198, v234, v204
	v_sub_f32_e32 v235, v198, v211
	v_cmp_lt_f32_e32 vcc, s81, v235
	s_or_b64 s[8:9], s[16:17], vcc
	s_cbranch_scc1 .Lp4_rare_00
.Lp4_back_00:
	v_sub_f32_e32 v80, v80, v211
	v_sub_f32_e32 v81, v81, v211
	v_sub_f32_e32 v82, v82, v211
	v_sub_f32_e32 v83, v83, v211
	v_exp_f32_e32 v80, v80
	v_exp_f32_e32 v81, v81
	v_exp_f32_e32 v82, v82
	v_mfma_f32_32x32x16_bf16 v[64:79], v[164:167], v[132:135], v[64:79]
	v_exp_f32_e32 v83, v83
	v_sub_f32_e32 v84, v84, v211
	v_sub_f32_e32 v85, v85, v211
	v_sub_f32_e32 v86, v86, v211
	v_sub_f32_e32 v87, v87, v211
	v_exp_f32_e32 v84, v84
	v_exp_f32_e32 v85, v85
	v_exp_f32_e32 v86, v86
	v_exp_f32_e32 v87, v87
	v_add_f32_e32 v198, v80, v84
	v_add_f32_e32 v199, v81, v85
	v_add_f32_e32 v204, v82, v86
	v_mfma_f32_32x32x16_bf16 v[64:79], v[160:163], v[140:143], v[64:79]
	v_add_f32_e32 v205, v83, v87
	v_sub_f32_e32 v88, v88, v211
	v_sub_f32_e32 v89, v89, v211
	v_sub_f32_e32 v90, v90, v211
	v_sub_f32_e32 v91, v91, v211
	v_exp_f32_e32 v88, v88
	v_exp_f32_e32 v89, v89
	v_exp_f32_e32 v90, v90
	v_exp_f32_e32 v91, v91
	v_add_f32_e32 v198, v198, v88
	v_add_f32_e32 v199, v199, v89
	v_add_f32_e32 v204, v204, v90
	v_mfma_f32_32x32x16_bf16 v[64:79], v[156:159], v[136:139], v[64:79]
	v_add_f32_e32 v205, v205, v91
	v_sub_f32_e32 v92, v92, v211
	v_sub_f32_e32 v93, v93, v211
	v_sub_f32_e32 v94, v94, v211
	v_sub_f32_e32 v95, v95, v211
	v_exp_f32_e32 v92, v92
	v_exp_f32_e32 v93, v93
	v_exp_f32_e32 v94, v94
	v_exp_f32_e32 v95, v95
	v_cvt_pk_bf16_f32 v80, v80, v81
	v_add_f32_e32 v198, v198, v92
	v_add_f32_e32 v199, v199, v93
	v_add_f32_e32 v204, v204, v94
	v_add_f32_e32 v205, v205, v95
	v_cvt_pk_bf16_f32 v81, v82, v83
	v_add_f32_e32 v198, v198, v199
	v_add_f32_e32 v204, v204, v205
	v_cvt_pk_bf16_f32 v82, v84, v85
	v_add_f32_e32 v198, v198, v204
	v_cvt_pk_bf16_f32 v83, v86, v87
	v_add_f32_e32 v212, v212, v198
	v_cvt_pk_bf16_f32 v84, v88, v89
	v_cvt_pk_bf16_f32 v85, v90, v91
	v_cvt_pk_bf16_f32 v86, v92, v93
	v_cvt_pk_bf16_f32 v87, v94, v95
	v_max3_f32 v198, v64, v65, v66
	v_max3_f32 v199, v67, v68, v69
	v_max3_f32 v204, v70, v71, v72
	s_waitcnt lgkmcnt(12)
	v_mfma_f32_32x32x16_bf16 v[48:63], v[192:195], v[80:83], v[48:63]
	v_max3_f32 v205, v73, v74, v75
	v_max3_f32 v234, v76, v77, v78
	s_waitcnt lgkmcnt(10)
	v_mfma_f32_32x32x16_bf16 v[32:47], v[188:191], v[80:83], v[32:47]
	v_max3_f32 v199, v198, v199, v204
	v_max3_f32 v205, v205, v234, v79
	s_waitcnt lgkmcnt(8)
	v_mfma_f32_32x32x16_bf16 v[48:63], v[184:187], v[84:87], v[48:63]
	v_max3_f32 v204, v199, v205, v198
	v_mov_b32_e32 v234, v204
	s_waitcnt lgkmcnt(6)
	v_mfma_f32_32x32x16_bf16 v[32:47], v[180:183], v[84:87], v[32:47]
	s_nop 1
	v_permlane32_swap_b32_e32 v234, v204
	v_max_f32_e32 v198, v234, v204
	v_sub_f32_e32 v235, v198, v223
	v_cmp_lt_f32_e32 vcc, s81, v235
	s_or_b64 s[8:9], s[100:101], vcc
	s_cbranch_scc1 .Lp4_rare_01
; #define LAS __attribute__((address_space(3)))
; template <int DQ, bool BIAS, bool TAIL>
; __device__ __forceinline__ void attn_item(const AttnItem& A, LAS unsigned char* lds, int wave_s_) {
;     ...
;         if (act) {
; #pragma unroll
;             for (int kbk = 0; kbk < 2; ++kbk) {
;                 __builtin_amdgcn_sched_barrier(0);
;                 f32x16 s[2];
;                 s[0] = MFMA32(kf[0], qf[0][0], zero16v); s[1] = MFMA32(kf[0], qf[1][0], zero16v);
; #pragma unroll
;                 for (int kk = 1; kk < NKK; ++kk) { s[0] = MFMA32(kf[kk], qf[0][kk], s[0]); s[1] = MFMA32(kf[kk], qf[1][kk], s[1]); }
;                 s16x4 vlo[2][2], vhi[2][2];
; #pragma unroll
;                 for (int st = 0; st < 2; ++st)
; #pragma unroll
;                     for (int d = 0; d < 2; ++d) { const LAS unsigned char* vp = vb + ((32 * kbk + 16 * st) * VROW + 32 * d) * 2; vlo[st][d] = vtr(vp); vhi[st][d] = vtr(vp + 8 * VROW * 2); }
;                 __builtin_amdgcn_sched_barrier(0);
;                 float mx[2];
; #pragma unroll
;                 for (int qb = 0; qb < 2; ++qb) {
;                     if (BIAS || TAIL) {
;                         const int qk = A.q_kidx0 + 64 * w + 32 * qb + r32;
; #pragma unroll
;                         for (int i = 0; i < 16; ++i) { const int kidx = 64 * t + 32 * kbk + crow(i, hi);
;                             float v = s[qb][i]; if (BIAS) v += lut[kidx - qk + LUT0]; if (TAIL && kidx >= A.nkeys) v = -1.0e30f; s[qb][i] = v; }
;                     }
;                     const float t0 = max3f(s[qb][0], s[qb][1], s[qb][2]), t1 = max3f(s[qb][3], s[qb][4], s[qb][5]), t2 = max3f(s[qb][6], s[qb][7], s[qb][8]),
;                                 t3 = max3f(s[qb][9], s[qb][10], s[qb][11]), t4 = max3f(s[qb][12], s[qb][13], s[qb][14]);
;                     const float m = max3f(max3f(t0, t1, t2), max3f(t3, t4, s[qb][15]), t0);
;                     mx[qb] = swapmax(m, hi) - mref[qb];
;                 }
;                 const bool need0 = first || mx[0] > RESCALE_THR, need1 = first || mx[1] > RESCALE_THR;
;                 if (__builtin_amdgcn_ballot_w64(need0 || need1) != 0ull) {
; #pragma unroll
;                     for (int qb = 0; qb < 2; ++qb) {
;                         const float delta = (qb == 0 ? need0 : need1) ? mx[qb] : 0.f, alpha = __builtin_amdgcn_exp2f(-delta);
; #pragma unroll
.Lp4_back_01:
	v_sub_f32_e32 v64, v64, v223
	s_waitcnt lgkmcnt(5)
	v_mfma_f32_32x32x16_bf16 v[80:95], v[230:233], v[96:99], 0
	v_sub_f32_e32 v65, v65, v223
	v_sub_f32_e32 v66, v66, v223
	v_sub_f32_e32 v67, v67, v223
	v_exp_f32_e32 v64, v64
	v_exp_f32_e32 v65, v65
	v_exp_f32_e32 v66, v66
	v_exp_f32_e32 v67, v67
	v_sub_f32_e32 v68, v68, v223
	v_sub_f32_e32 v69, v69, v223
	s_waitcnt lgkmcnt(4)
	v_mfma_f32_32x32x16_bf16 v[80:95], v[238:241], v[100:103], v[80:95]
	v_sub_f32_e32 v70, v70, v223
	v_sub_f32_e32 v71, v71, v223
	v_exp_f32_e32 v68, v68
	v_exp_f32_e32 v69, v69
	v_exp_f32_e32 v70, v70
	v_exp_f32_e32 v71, v71
	v_add_f32_e32 v198, v64, v68
	v_add_f32_e32 v199, v65, v69
	v_add_f32_e32 v204, v66, v70
	s_waitcnt lgkmcnt(3)
	v_mfma_f32_32x32x16_bf16 v[80:95], v[246:249], v[104:107], v[80:95]
	v_add_f32_e32 v205, v67, v71
	v_sub_f32_e32 v72, v72, v223
	v_sub_f32_e32 v73, v73, v223
	v_sub_f32_e32 v74, v74, v223
	v_sub_f32_e32 v75, v75, v223
	v_exp_f32_e32 v72, v72
	v_exp_f32_e32 v73, v73
	v_exp_f32_e32 v74, v74
	v_exp_f32_e32 v75, v75
	s_waitcnt lgkmcnt(2)
	v_mfma_f32_32x32x16_bf16 v[80:95], v[250:253], v[108:111], v[80:95]
	v_add_f32_e32 v198, v198, v72
	v_add_f32_e32 v199, v199, v73
	v_add_f32_e32 v204, v204, v74
	v_add_f32_e32 v205, v205, v75
	v_sub_f32_e32 v76, v76, v223
	v_sub_f32_e32 v77, v77, v223
	v_sub_f32_e32 v78, v78, v223
	v_sub_f32_e32 v79, v79, v223
	v_exp_f32_e32 v76, v76
	s_waitcnt lgkmcnt(1)
	v_mfma_f32_32x32x16_bf16 v[80:95], v[176:179], v[112:115], v[80:95]
	v_exp_f32_e32 v77, v77
	v_exp_f32_e32 v78, v78
	v_exp_f32_e32 v79, v79
	v_cvt_pk_bf16_f32 v64, v64, v65
	v_add_f32_e32 v198, v198, v76
	v_add_f32_e32 v199, v199, v77
	v_add_f32_e32 v204, v204, v78
	s_waitcnt lgkmcnt(0)
	v_mfma_f32_32x32x16_bf16 v[80:95], v[172:175], v[116:119], v[80:95]
	v_add_f32_e32 v205, v205, v79
	v_cvt_pk_bf16_f32 v65, v66, v67
	v_add_f32_e32 v198, v198, v199
	v_add_f32_e32 v204, v204, v205
	v_cvt_pk_bf16_f32 v66, v68, v69
	v_add_f32_e32 v198, v198, v204
	v_cvt_pk_bf16_f32 v67, v70, v71
	v_add_f32_e32 v213, v213, v198
	v_cvt_pk_bf16_f32 v68, v72, v73
	v_cvt_pk_bf16_f32 v69, v74, v75
	v_cvt_pk_bf16_f32 v70, v76, v77
	v_cvt_pk_bf16_f32 v71, v78, v79
	v_max3_f32 v198, v80, v81, v82
	v_max3_f32 v199, v83, v84, v85
	v_max3_f32 v204, v86, v87, v88
	v_mfma_f32_32x32x16_bf16 v[16:31], v[192:195], v[64:67], v[16:31]
	v_max3_f32 v205, v89, v90, v91
	v_max3_f32 v234, v92, v93, v94
	v_mfma_f32_32x32x16_bf16 v[0:15], v[188:191], v[64:67], v[0:15]
	v_max3_f32 v199, v198, v199, v204
	v_max3_f32 v205, v205, v234, v95
	v_mfma_f32_32x32x16_bf16 v[16:31], v[184:187], v[68:71], v[16:31]
	v_max3_f32 v204, v199, v205, v198
	v_mov_b32_e32 v234, v204
	v_mfma_f32_32x32x16_bf16 v[0:15], v[180:183], v[68:71], v[0:15]
	ds_read_b64_tr_b16 v[192:193], v229 offset:31232
	ds_read_b64_tr_b16 v[194:195], v229 offset:32384
	ds_read_b64_tr_b16 v[188:189], v229 offset:31296
	ds_read_b64_tr_b16 v[190:191], v229 offset:32448
	ds_read_b64_tr_b16 v[184:185], v229 offset:33536
	ds_read_b64_tr_b16 v[186:187], v229 offset:34688
	ds_read_b64_tr_b16 v[180:181], v229 offset:33600
	ds_read_b64_tr_b16 v[182:183], v229 offset:34752
	s_nop 1
	v_permlane32_swap_b32_e32 v234, v204
	v_max_f32_e32 v198, v234, v204
	v_sub_f32_e32 v235, v198, v211
	v_cmp_lt_f32_e32 vcc, s81, v235
	s_or_b64 s[8:9], s[16:17], vcc
	s_cbranch_scc1 .Lp4_rare_10
.Lp4_back_10:
	v_sub_f32_e32 v80, v80, v211
	v_mfma_f32_32x32x16_bf16 v[64:79], v[230:233], v[120:123], 0
	v_sub_f32_e32 v81, v81, v211
	v_sub_f32_e32 v82, v82, v211
	v_sub_f32_e32 v83, v83, v211
	v_exp_f32_e32 v80, v80
	v_exp_f32_e32 v81, v81
	v_exp_f32_e32 v82, v82
	v_exp_f32_e32 v83, v83
	v_sub_f32_e32 v84, v84, v211
	v_sub_f32_e32 v85, v85, v211
	v_mfma_f32_32x32x16_bf16 v[64:79], v[238:241], v[124:127], v[64:79]
	v_sub_f32_e32 v86, v86, v211
	v_sub_f32_e32 v87, v87, v211
	v_exp_f32_e32 v84, v84
	v_exp_f32_e32 v85, v85
	v_exp_f32_e32 v86, v86
	v_exp_f32_e32 v87, v87
	v_add_f32_e32 v198, v80, v84
	v_add_f32_e32 v199, v81, v85
	v_add_f32_e32 v204, v82, v86
	v_mfma_f32_32x32x16_bf16 v[64:79], v[246:249], v[128:131], v[64:79]
	v_add_f32_e32 v205, v83, v87
	v_sub_f32_e32 v88, v88, v211
	v_sub_f32_e32 v89, v89, v211
	v_sub_f32_e32 v90, v90, v211
	v_sub_f32_e32 v91, v91, v211
	v_exp_f32_e32 v88, v88
	v_exp_f32_e32 v89, v89
	v_exp_f32_e32 v90, v90
	v_exp_f32_e32 v91, v91
	v_mfma_f32_32x32x16_bf16 v[64:79], v[250:253], v[132:135], v[64:79]
	v_add_f32_e32 v198, v198, v88
	v_add_f32_e32 v199, v199, v89
	v_add_f32_e32 v204, v204, v90
	v_add_f32_e32 v205, v205, v91
	v_sub_f32_e32 v92, v92, v211
	v_sub_f32_e32 v93, v93, v211
	v_sub_f32_e32 v94, v94, v211
	v_sub_f32_e32 v95, v95, v211
	v_exp_f32_e32 v92, v92
	v_mfma_f32_32x32x16_bf16 v[64:79], v[176:179], v[140:143], v[64:79]
	v_exp_f32_e32 v93, v93
	v_exp_f32_e32 v94, v94
	v_exp_f32_e32 v95, v95
	v_cvt_pk_bf16_f32 v80, v80, v81
	v_add_f32_e32 v198, v198, v92
	v_add_f32_e32 v199, v199, v93
	v_add_f32_e32 v204, v204, v94
	v_mfma_f32_32x32x16_bf16 v[64:79], v[172:175], v[136:139], v[64:79]
	v_add_f32_e32 v205, v205, v95
	v_cvt_pk_bf16_f32 v81, v82, v83
	v_add_f32_e32 v198, v198, v199
	v_add_f32_e32 v204, v204, v205
	v_cvt_pk_bf16_f32 v82, v84, v85
	v_add_f32_e32 v198, v198, v204
	v_cvt_pk_bf16_f32 v83, v86, v87
	v_add_f32_e32 v212, v212, v198
	v_cvt_pk_bf16_f32 v84, v88, v89
	v_cvt_pk_bf16_f32 v85, v90, v91
	v_cvt_pk_bf16_f32 v86, v92, v93
	v_cvt_pk_bf16_f32 v87, v94, v95
	v_max3_f32 v198, v64, v65, v66
	v_max3_f32 v199, v67, v68, v69
	v_max3_f32 v204, v70, v71, v72
	v_max3_f32 v205, v73, v74, v75
	v_max3_f32 v234, v76, v77, v78
	v_max3_f32 v199, v198, v199, v204
	v_max3_f32 v205, v205, v234, v79
	v_max3_f32 v204, v199, v205, v198
	v_mov_b32_e32 v234, v204
	s_nop 1
	v_permlane32_swap_b32_e32 v234, v204
	s_waitcnt lgkmcnt(6)
	v_mfma_f32_32x32x16_bf16 v[48:63], v[192:195], v[80:83], v[48:63]
	v_max_f32_e32 v198, v234, v204
	v_sub_f32_e32 v235, v198, v223
	v_cmp_lt_f32_e32 vcc, s81, v235
	s_or_b64 s[8:9], s[100:101], vcc
	s_cbranch_scc1 .Lp4_rare_11
; #define LAS __attribute__((address_space(3)))
; __device__ __forceinline__ unsigned pk2c(float lo, float hi) { f32x2_t v = {lo, hi}; bf16x2_t b = __builtin_convertvector(v, bf16x2_t); return __builtin_bit_cast(unsigned, b); }
; template <int DQ, bool BIAS, bool TAIL>
; __device__ __forceinline__ void attn_item(const AttnItem& A, LAS unsigned char* lds, int wave_s_) {
;     ...
;                 const bool need0 = first || mx[0] > RESCALE_THR, need1 = first || mx[1] > RESCALE_THR;
;                 if (__builtin_amdgcn_ballot_w64(need0 || need1) != 0ull) {
; #pragma unroll
;                     for (int qb = 0; qb < 2; ++qb) {
;                         const float delta = (qb == 0 ? need0 : need1) ? mx[qb] : 0.f, alpha = __builtin_amdgcn_exp2f(-delta);
; #pragma unroll
;                         for (int i = 0; i < 16; ++i) { o[0][qb][i] *= alpha; o[1][qb][i] *= alpha; }
;                         lrun[qb] *= alpha; mref[qb] += delta;
;                     }
;                     first = false;
;                 }
;     ...
;                 for (int qb = 0; qb < 2; ++qb) { float l4[4] = {0.f, 0.f, 0.f, 0.f};
; #pragma unroll
;                     for (int i = 0; i < 16; ++i) { const float pv = __builtin_amdgcn_exp2f(s[qb][i] - mref[qb]); s[qb][i] = pv; l4[i & 3] += pv; }
;                     lrun[qb] += (l4[0] + l4[1]) + (l4[2] + l4[3]); }
;                 bf16x8 pf[2][2];
; #pragma unroll
;                 for (int st = 0; st < 2; ++st)
; #pragma unroll
;                     for (int qb = 0; qb < 2; ++qb) { u32x4 pw;
; #pragma unroll
;                         for (int j = 0; j < 4; ++j) pw[j] = pk2c(s[qb][8 * st + 2 * j], s[qb][8 * st + 2 * j + 1]);
;                         pf[st][qb] = __builtin_bit_cast(bf16x8, pw); }
;                 if (kbk == 0) {
; #pragma unroll
;                     for (int kk = 0; kk < NKK; ++kk) kf[kk] = *(const LAS bf16x8*)(kb + (32 * KSTR + 16 * kk) * 2);
;                 }
;                 __builtin_amdgcn_sched_barrier(0);
; #pragma unroll
;                 for (int st = 0; st < 2; ++st)
; #pragma unroll
;                     for (int d = 0; d < 2; ++d) {
;                         const bf16x8 vf = __builtin_shufflevector(vlo[st][d], vhi[st][d], 0, 1, 2, 3, 4, 5, 6, 7);
;                         o[d][0] = MFMA32(vf, pf[st][0], o[d][0]);
;                         o[d][1] = MFMA32(vf, pf[st][1], o[d][1]);
;                     }
.Lp4_back_11:
	v_sub_f32_e32 v64, v64, v223
	v_sub_f32_e32 v65, v65, v223
	v_sub_f32_e32 v66, v66, v223
	v_sub_f32_e32 v67, v67, v223
	v_exp_f32_e32 v64, v64
	v_exp_f32_e32 v65, v65
	v_exp_f32_e32 v66, v66
	v_exp_f32_e32 v67, v67
	v_sub_f32_e32 v68, v68, v223
	v_sub_f32_e32 v69, v69, v223
	v_sub_f32_e32 v70, v70, v223
	s_waitcnt lgkmcnt(4)
	v_mfma_f32_32x32x16_bf16 v[32:47], v[188:191], v[80:83], v[32:47]
	v_sub_f32_e32 v71, v71, v223
	v_exp_f32_e32 v68, v68
	v_exp_f32_e32 v69, v69
	v_exp_f32_e32 v70, v70
	v_exp_f32_e32 v71, v71
	v_add_f32_e32 v198, v64, v68
	v_add_f32_e32 v199, v65, v69
	v_add_f32_e32 v204, v66, v70
	v_add_f32_e32 v205, v67, v71
	v_sub_f32_e32 v72, v72, v223
	v_sub_f32_e32 v73, v73, v223
	v_sub_f32_e32 v74, v74, v223
	v_sub_f32_e32 v75, v75, v223
	v_exp_f32_e32 v72, v72
	s_waitcnt lgkmcnt(2)
	v_mfma_f32_32x32x16_bf16 v[48:63], v[184:187], v[84:87], v[48:63]
	v_exp_f32_e32 v73, v73
	v_exp_f32_e32 v74, v74
	v_exp_f32_e32 v75, v75
	v_add_f32_e32 v198, v198, v72
	v_add_f32_e32 v199, v199, v73
	v_add_f32_e32 v204, v204, v74
	v_add_f32_e32 v205, v205, v75
	v_sub_f32_e32 v76, v76, v223
	v_sub_f32_e32 v77, v77, v223
	v_sub_f32_e32 v78, v78, v223
	v_sub_f32_e32 v79, v79, v223
	v_exp_f32_e32 v76, v76
	v_exp_f32_e32 v77, v77
	v_exp_f32_e32 v78, v78
	s_waitcnt lgkmcnt(0)
	v_mfma_f32_32x32x16_bf16 v[32:47], v[180:183], v[84:87], v[32:47]
	v_exp_f32_e32 v79, v79
	v_cvt_pk_bf16_f32 v64, v64, v65
	v_add_f32_e32 v198, v198, v76
	v_add_f32_e32 v199, v199, v77
	v_add_f32_e32 v204, v204, v78
	v_add_f32_e32 v205, v205, v79
	v_cvt_pk_bf16_f32 v65, v66, v67
	v_add_f32_e32 v198, v198, v199
	v_add_f32_e32 v204, v204, v205
	v_cvt_pk_bf16_f32 v66, v68, v69
	v_add_f32_e32 v198, v198, v204
	v_cvt_pk_bf16_f32 v67, v70, v71
	v_add_f32_e32 v213, v213, v198
	v_cvt_pk_bf16_f32 v68, v72, v73
	v_cvt_pk_bf16_f32 v69, v74, v75
	v_cvt_pk_bf16_f32 v70, v76, v77
	v_cvt_pk_bf16_f32 v71, v78, v79
	s_nop 1
	v_mfma_f32_32x32x16_bf16 v[16:31], v[192:195], v[64:67], v[16:31]
	v_mfma_f32_32x32x16_bf16 v[0:15], v[188:191], v[64:67], v[0:15]
	v_mfma_f32_32x32x16_bf16 v[16:31], v[184:187], v[68:71], v[16:31]
	v_mfma_f32_32x32x16_bf16 v[0:15], v[180:183], v[68:71], v[0:15]
	s_branch .LBB0_1484
.Lp4_rare_00:
	s_nop 15
	v_cndmask_b32_e64 v234, 0, v235, s[8:9]
	v_exp_f32_e64 v198, -v234
	v_add_f32_e32 v211, v211, v234
	s_nop 0
	v_pk_mul_f32 v[62:63], v[62:63], v[198:199] op_sel_hi:[1,0]
	v_pk_mul_f32 v[60:61], v[60:61], v[198:199] op_sel_hi:[1,0]
	v_pk_mul_f32 v[58:59], v[58:59], v[198:199] op_sel_hi:[1,0]
	v_pk_mul_f32 v[56:57], v[56:57], v[198:199] op_sel_hi:[1,0]
	v_pk_mul_f32 v[54:55], v[54:55], v[198:199] op_sel_hi:[1,0]
	v_pk_mul_f32 v[52:53], v[52:53], v[198:199] op_sel_hi:[1,0]
	v_pk_mul_f32 v[50:51], v[50:51], v[198:199] op_sel_hi:[1,0]
	v_pk_mul_f32 v[48:49], v[48:49], v[198:199] op_sel_hi:[1,0]
	v_pk_mul_f32 v[46:47], v[46:47], v[198:199] op_sel_hi:[1,0]
	v_pk_mul_f32 v[44:45], v[44:45], v[198:199] op_sel_hi:[1,0]
	v_pk_mul_f32 v[42:43], v[42:43], v[198:199] op_sel_hi:[1,0]
	v_pk_mul_f32 v[40:41], v[40:41], v[198:199] op_sel_hi:[1,0]
	v_pk_mul_f32 v[38:39], v[38:39], v[198:199] op_sel_hi:[1,0]
	v_pk_mul_f32 v[36:37], v[36:37], v[198:199] op_sel_hi:[1,0]
	v_pk_mul_f32 v[34:35], v[34:35], v[198:199] op_sel_hi:[1,0]
	v_pk_mul_f32 v[32:33], v[32:33], v[198:199] op_sel_hi:[1,0]
	v_mul_f32_e32 v212, v212, v198
	s_mov_b64 s[16:17], 0
	s_branch .Lp4_back_00
.Lp4_rare_01:
	s_nop 15
	v_cndmask_b32_e64 v234, 0, v235, s[8:9]
	v_exp_f32_e64 v198, -v234
	v_add_f32_e32 v223, v223, v234
	s_nop 0
	v_pk_mul_f32 v[30:31], v[30:31], v[198:199] op_sel_hi:[1,0]
	v_pk_mul_f32 v[28:29], v[28:29], v[198:199] op_sel_hi:[1,0]
	v_pk_mul_f32 v[26:27], v[26:27], v[198:199] op_sel_hi:[1,0]
	v_pk_mul_f32 v[24:25], v[24:25], v[198:199] op_sel_hi:[1,0]
	v_pk_mul_f32 v[22:23], v[22:23], v[198:199] op_sel_hi:[1,0]
	v_pk_mul_f32 v[20:21], v[20:21], v[198:199] op_sel_hi:[1,0]
	v_pk_mul_f32 v[18:19], v[18:19], v[198:199] op_sel_hi:[1,0]
	v_pk_mul_f32 v[16:17], v[16:17], v[198:199] op_sel_hi:[1,0]
	v_pk_mul_f32 v[14:15], v[14:15], v[198:199] op_sel_hi:[1,0]
	v_pk_mul_f32 v[12:13], v[12:13], v[198:199] op_sel_hi:[1,0]
	v_pk_mul_f32 v[10:11], v[10:11], v[198:199] op_sel_hi:[1,0]
	v_pk_mul_f32 v[8:9], v[8:9], v[198:199] op_sel_hi:[1,0]
	v_pk_mul_f32 v[6:7], v[6:7], v[198:199] op_sel_hi:[1,0]
	v_pk_mul_f32 v[4:5], v[4:5], v[198:199] op_sel_hi:[1,0]
	v_pk_mul_f32 v[2:3], v[2:3], v[198:199] op_sel_hi:[1,0]
	v_pk_mul_f32 v[0:1], v[0:1], v[198:199] op_sel_hi:[1,0]
	v_mul_f32_e32 v213, v213, v198
	s_mov_b64 s[100:101], 0
	s_branch .Lp4_back_01

; #define LAS __attribute__((address_space(3)))
; __device__ __forceinline__ ArgsP get_args() { ArgsP p = (ArgsP)__builtin_amdgcn_kernarg_segment_ptr(); asm volatile("" : "+s"(p)); return p; }
; __global__ void __launch_bounds__(NT, 2) fwd_megakernel(Args a_unused) {
;     extern __shared__ __attribute__((aligned(16))) unsigned char lds_raw[];
;     LAS unsigned char* lds = (LAS unsigned char*)lds_raw;
;     cg::grid_group grid = cg::this_grid();
;     if (threadIdx.x < 4) ((LAS unsigned*)(lds + LDS_BYTES - 16))[threadIdx.x] = 0u;
;     __syncthreads();
;     (void)xcd_barrier_post((unsigned*)(get_args()->ws + WS_CTL), (volatile LAS unsigned*)(lds + LDS_BYTES - 16));
;     ...
;     const int wave_s_ = __builtin_amdgcn_readfirstlane((int)threadIdx.x >> 6);
	.amdhsa_kernel _Z14fwd_megakernel4Args
		.amdhsa_group_segment_fixed_size 0
		.amdhsa_private_segment_fixed_size 0
		.amdhsa_kernarg_size 496
		.amdhsa_user_sgpr_count 2
		.amdhsa_user_sgpr_dispatch_ptr 0
		.amdhsa_user_sgpr_queue_ptr 0
		.amdhsa_user_sgpr_kernarg_segment_ptr 1
		.amdhsa_user_sgpr_dispatch_id 0
		.amdhsa_user_sgpr_kernarg_preload_length 0
		.amdhsa_user_sgpr_kernarg_preload_offset 0
		.amdhsa_user_sgpr_private_segment_size 0
		.amdhsa_uses_dynamic_stack 0
		.amdhsa_enable_private_segment 0
		.amdhsa_system_sgpr_workgroup_id_x 1
		.amdhsa_system_sgpr_workgroup_id_y 0
		.amdhsa_system_sgpr_workgroup_id_z 0
		.amdhsa_system_sgpr_workgroup_info 0
		.amdhsa_system_vgpr_workitem_id 2
		.amdhsa_next_free_vgpr 256
		.amdhsa_next_free_sgpr 102
		.amdhsa_accum_offset 256
		.amdhsa_reserve_vcc 1
		.amdhsa_float_round_mode_32 0
		.amdhsa_float_round_mode_16_64 0
		.amdhsa_float_denorm_mode_32 3
		.amdhsa_float_denorm_mode_16_64 3
		.amdhsa_dx10_clamp 1
		.amdhsa_ieee_mode 1
		.amdhsa_fp16_overflow 0
		.amdhsa_tg_split 0
		.amdhsa_exception_fp_ieee_invalid_op 0
		.amdhsa_exception_fp_denorm_src 0
		.amdhsa_exception_fp_ieee_div_zero 0
		.amdhsa_exception_fp_ieee_overflow 0
		.amdhsa_exception_fp_ieee_underflow 0
		.amdhsa_exception_fp_ieee_inexact 0
		.amdhsa_exception_int_div_zero 0
	.end_amdhsa_kernel

; #define LAS __attribute__((address_space(3)))
; __device__ __forceinline__ ArgsP get_args() { ArgsP p = (ArgsP)__builtin_amdgcn_kernarg_segment_ptr(); asm volatile("" : "+s"(p)); return p; }
; __global__ void __launch_bounds__(NT, 2) fwd_megakernel(Args a_unused) {
;     extern __shared__ __attribute__((aligned(16))) unsigned char lds_raw[];
;     LAS unsigned char* lds = (LAS unsigned char*)lds_raw;
;     cg::grid_group grid = cg::this_grid();
;     if (threadIdx.x < 4) ((LAS unsigned*)(lds + LDS_BYTES - 16))[threadIdx.x] = 0u;
;     __syncthreads();
;     (void)xcd_barrier_post((unsigned*)(get_args()->ws + WS_CTL), (volatile LAS unsigned*)(lds + LDS_BYTES - 16));
;     ...
;     const int wave_s_ = __builtin_amdgcn_readfirstlane((int)threadIdx.x >> 6);
amdhsa.kernels:
  - .agpr_count:     0
    .args:
      - .offset:         0
        .size:           240
        .value_kind:     by_value
      - .offset:         240
        .size:           4
        .value_kind:     hidden_block_count_x
      - .offset:         244
        .size:           4
        .value_kind:     hidden_block_count_y
      - .offset:         248
        .size:           4
        .value_kind:     hidden_block_count_z
      - .offset:         252
        .size:           2
        .value_kind:     hidden_group_size_x
      - .offset:         254
        .size:           2
        .value_kind:     hidden_group_size_y
      - .offset:         256
        .size:           2
        .value_kind:     hidden_group_size_z
      - .offset:         258
        .size:           2
        .value_kind:     hidden_remainder_x
      - .offset:         260
        .size:           2
        .value_kind:     hidden_remainder_y
      - .offset:         262
        .size:           2
        .value_kind:     hidden_remainder_z
      - .offset:         280
        .size:           8
        .value_kind:     hidden_global_offset_x
      - .offset:         288
        .size:           8
        .value_kind:     hidden_global_offset_y
      - .offset:         296
        .size:           8
        .value_kind:     hidden_global_offset_z
      - .offset:         304
        .size:           2
        .value_kind:     hidden_grid_dims
      - .offset:         328
        .size:           8
        .value_kind:     hidden_multigrid_sync_arg
      - .offset:         360
        .size:           4
        .value_kind:     hidden_dynamic_lds_size
    .group_segment_fixed_size: 0
    .kernarg_segment_align: 8
    .kernarg_segment_size: 496
    .language:       OpenCL C
    .language_version:
      - 2
      - 0
    .max_flat_workgroup_size: 512
    .name:           _Z14fwd_megakernel4Args
    .private_segment_fixed_size: 0
    .sgpr_count:     108
    .sgpr_spill_count: 46
    .symbol:         _Z14fwd_megakernel4Args.kd
    .uniform_work_group_size: 1
    .uses_dynamic_stack: false
    .vgpr_count:     256
    .vgpr_spill_count: 0
    .wavefront_size: 64
